# v55 + the five GEMM K-loop heads aligned to 64 bytes (.p2align 6; code placement)
# baseline (speedup 1.0000x reference)
.LBB0_123:
	s_ashr_i32 s51, s50, 31
	s_lshl_b64 s[22:23], s[50:51], 21
	s_add_u32 s52, s66, s22
	s_addc_u32 s53, s67, s23
	s_and_b64 s[22:23], s[12:13], exec
	s_cselect_b32 s15, s53, s17
	s_cselect_b32 s21, s52, s16
	s_ashr_i32 s49, s48, 31
	s_lshl_b64 s[22:23], s[48:49], 21
	s_add_u32 s54, s68, s22
	s_addc_u32 s55, s69, s23
	s_and_b64 s[22:23], s[12:13], exec
	s_cselect_b32 s24, s55, s19
	s_cselect_b32 s25, s54, s18
	s_add_u32 s16, s16, 0x100080
	s_addc_u32 s17, s17, 0
	s_add_u32 s49, s18, 0x100
	v_mov_b32_e32 v0, 0
	s_addc_u32 s51, s19, 0
	s_mov_b32 s56, -2
	v_mov_b32_e32 v1, v0
	v_mov_b32_e32 v2, v0
	v_mov_b32_e32 v3, v0
	v_mov_b32_e32 v4, v0
	v_mov_b32_e32 v5, v0
	v_mov_b32_e32 v6, v0
	v_mov_b32_e32 v7, v0
	v_mov_b32_e32 v16, v0
	v_mov_b32_e32 v17, v0
	v_mov_b32_e32 v18, v0
	v_mov_b32_e32 v19, v0
	v_mov_b32_e32 v20, v0
	v_mov_b32_e32 v21, v0
	v_mov_b32_e32 v22, v0
	v_mov_b32_e32 v23, v0
	v_mov_b32_e32 v32, v0
	v_mov_b32_e32 v33, v0
	v_mov_b32_e32 v34, v0
	v_mov_b32_e32 v35, v0
	v_mov_b32_e32 v36, v0
	v_mov_b32_e32 v37, v0
	v_mov_b32_e32 v38, v0
	v_mov_b32_e32 v39, v0
	v_mov_b32_e32 v48, v0
	v_mov_b32_e32 v49, v0
	v_mov_b32_e32 v50, v0
	v_mov_b32_e32 v51, v0
	v_mov_b32_e32 v52, v0
	v_mov_b32_e32 v53, v0
	v_mov_b32_e32 v54, v0
	v_mov_b32_e32 v55, v0
	v_mov_b32_e32 v8, v0
	v_mov_b32_e32 v9, v0
	v_mov_b32_e32 v10, v0
	v_mov_b32_e32 v11, v0
	v_mov_b32_e32 v12, v0
	v_mov_b32_e32 v13, v0
	v_mov_b32_e32 v14, v0
	v_mov_b32_e32 v15, v0
	v_mov_b32_e32 v24, v0
	v_mov_b32_e32 v25, v0
	v_mov_b32_e32 v26, v0
	v_mov_b32_e32 v27, v0
	v_mov_b32_e32 v28, v0
	v_mov_b32_e32 v29, v0
	v_mov_b32_e32 v30, v0
	v_mov_b32_e32 v31, v0
	v_mov_b32_e32 v40, v0
	v_mov_b32_e32 v41, v0
	v_mov_b32_e32 v42, v0
	v_mov_b32_e32 v43, v0
	v_mov_b32_e32 v44, v0
	v_mov_b32_e32 v45, v0
	v_mov_b32_e32 v46, v0
	v_mov_b32_e32 v47, v0
	v_mov_b32_e32 v56, v0
	v_mov_b32_e32 v57, v0
	v_mov_b32_e32 v58, v0
	v_mov_b32_e32 v59, v0
	v_mov_b32_e32 v60, v0
	v_mov_b32_e32 v61, v0
	v_mov_b32_e32 v62, v0
	v_mov_b32_e32 v63, v0
	v_mov_b32_e32 v64, v0
	v_mov_b32_e32 v65, v0
	v_mov_b32_e32 v66, v0
	v_mov_b32_e32 v67, v0
	v_mov_b32_e32 v68, v0
	v_mov_b32_e32 v69, v0
	v_mov_b32_e32 v70, v0
	v_mov_b32_e32 v71, v0
	v_mov_b32_e32 v80, v0
	v_mov_b32_e32 v81, v0
	v_mov_b32_e32 v82, v0
	v_mov_b32_e32 v83, v0
	v_mov_b32_e32 v84, v0
	v_mov_b32_e32 v85, v0
	v_mov_b32_e32 v86, v0
	v_mov_b32_e32 v87, v0
	v_mov_b32_e32 v96, v0
	v_mov_b32_e32 v97, v0
	v_mov_b32_e32 v98, v0
	v_mov_b32_e32 v99, v0
	v_mov_b32_e32 v100, v0
	v_mov_b32_e32 v101, v0
	v_mov_b32_e32 v102, v0
	v_mov_b32_e32 v103, v0
	v_mov_b32_e32 v112, v0
	v_mov_b32_e32 v113, v0
	v_mov_b32_e32 v114, v0
	v_mov_b32_e32 v115, v0
	v_mov_b32_e32 v116, v0
	v_mov_b32_e32 v117, v0
	v_mov_b32_e32 v118, v0
	v_mov_b32_e32 v119, v0
	v_mov_b32_e32 v72, v0
	v_mov_b32_e32 v73, v0
	v_mov_b32_e32 v74, v0
	v_mov_b32_e32 v75, v0
	v_mov_b32_e32 v76, v0
	v_mov_b32_e32 v77, v0
	v_mov_b32_e32 v78, v0
	v_mov_b32_e32 v79, v0
	v_mov_b32_e32 v88, v0
	v_mov_b32_e32 v89, v0
	v_mov_b32_e32 v90, v0
	v_mov_b32_e32 v91, v0
	v_mov_b32_e32 v92, v0
	v_mov_b32_e32 v93, v0
	v_mov_b32_e32 v94, v0
	v_mov_b32_e32 v95, v0
	v_mov_b32_e32 v104, v0
	v_mov_b32_e32 v105, v0
	v_mov_b32_e32 v106, v0
	v_mov_b32_e32 v107, v0
	v_mov_b32_e32 v108, v0
	v_mov_b32_e32 v109, v0
	v_mov_b32_e32 v110, v0
	v_mov_b32_e32 v111, v0
	v_mov_b32_e32 v120, v0
	v_mov_b32_e32 v121, v0
	v_mov_b32_e32 v122, v0
	v_mov_b32_e32 v123, v0
	v_mov_b32_e32 v124, v0
	v_mov_b32_e32 v125, v0
	v_mov_b32_e32 v126, v0
	v_mov_b32_e32 v127, v0
	.p2align 6

.LBB0_1153:
	s_mov_b32 s34, s31
	s_mov_b32 s30, s35
	s_ashr_i32 s35, s31, 31
	s_lshl_b64 s[38:39], s[34:35], 21
	s_add_u32 s31, s25, s38
	s_mov_b32 s28, s40
	s_mov_b32 s74, s29
	s_addc_u32 s35, s50, s39
	s_ashr_i32 s29, s40, 31
	s_mov_b32 s73, s41
	s_lshl_b64 s[40:41], s[28:29], 7
	s_add_u32 s38, s31, s40
	s_addc_u32 s39, s35, s41
	s_and_b64 s[48:49], s[36:37], exec
	s_cselect_b32 s29, s39, s45
	s_cselect_b32 s35, s38, s44
	s_ashr_i32 s31, s30, 31
	s_lshl_b64 s[48:49], s[30:31], 21
	s_add_u32 s31, s51, s48
	s_addc_u32 s43, s52, s49
	s_add_u32 s40, s31, s40
	s_addc_u32 s41, s43, s41
	s_and_b64 s[48:49], s[36:37], exec
	s_cselect_b32 s31, s41, s47
	s_cselect_b32 s43, s40, s46
	s_add_i32 s75, s27, -2
	s_add_u32 s44, s44, 0x100080
	s_addc_u32 s45, s45, 0
	s_add_u32 s76, s46, 0x100
	v_mov_b32_e32 v0, 0
	s_addc_u32 s77, s47, 0
	s_mov_b32 s46, 0
	v_mov_b32_e32 v1, v0
	v_mov_b32_e32 v2, v0
	v_mov_b32_e32 v3, v0
	v_mov_b32_e32 v4, v0
	v_mov_b32_e32 v5, v0
	v_mov_b32_e32 v6, v0
	v_mov_b32_e32 v7, v0
	v_mov_b32_e32 v12, v0
	v_mov_b32_e32 v13, v0
	v_mov_b32_e32 v14, v0
	v_mov_b32_e32 v15, v0
	v_mov_b32_e32 v16, v0
	v_mov_b32_e32 v17, v0
	v_mov_b32_e32 v18, v0
	v_mov_b32_e32 v19, v0
	v_mov_b32_e32 v28, v0
	v_mov_b32_e32 v29, v0
	v_mov_b32_e32 v30, v0
	v_mov_b32_e32 v31, v0
	v_mov_b32_e32 v32, v0
	v_mov_b32_e32 v33, v0
	v_mov_b32_e32 v34, v0
	v_mov_b32_e32 v35, v0
	v_mov_b32_e32 v44, v0
	v_mov_b32_e32 v45, v0
	v_mov_b32_e32 v46, v0
	v_mov_b32_e32 v47, v0
	v_mov_b32_e32 v48, v0
	v_mov_b32_e32 v49, v0
	v_mov_b32_e32 v50, v0
	v_mov_b32_e32 v51, v0
	v_mov_b32_e32 v8, v0
	v_mov_b32_e32 v9, v0
	v_mov_b32_e32 v10, v0
	v_mov_b32_e32 v11, v0
	v_mov_b32_e32 v20, v0
	v_mov_b32_e32 v21, v0
	v_mov_b32_e32 v22, v0
	v_mov_b32_e32 v23, v0
	v_mov_b32_e32 v24, v0
	v_mov_b32_e32 v25, v0
	v_mov_b32_e32 v26, v0
	v_mov_b32_e32 v27, v0
	v_mov_b32_e32 v36, v0
	v_mov_b32_e32 v37, v0
	v_mov_b32_e32 v38, v0
	v_mov_b32_e32 v39, v0
	v_mov_b32_e32 v40, v0
	v_mov_b32_e32 v41, v0
	v_mov_b32_e32 v42, v0
	v_mov_b32_e32 v43, v0
	v_mov_b32_e32 v52, v0
	v_mov_b32_e32 v53, v0
	v_mov_b32_e32 v54, v0
	v_mov_b32_e32 v55, v0
	v_mov_b32_e32 v56, v0
	v_mov_b32_e32 v57, v0
	v_mov_b32_e32 v58, v0
	v_mov_b32_e32 v59, v0
	v_mov_b32_e32 v60, v0
	v_mov_b32_e32 v61, v0
	v_mov_b32_e32 v62, v0
	v_mov_b32_e32 v63, v0
	v_mov_b32_e32 v64, v0
	v_mov_b32_e32 v65, v0
	v_mov_b32_e32 v66, v0
	v_mov_b32_e32 v67, v0
	v_mov_b32_e32 v68, v0
	v_mov_b32_e32 v69, v0
	v_mov_b32_e32 v70, v0
	v_mov_b32_e32 v71, v0
	v_mov_b32_e32 v72, v0
	v_mov_b32_e32 v73, v0
	v_mov_b32_e32 v74, v0
	v_mov_b32_e32 v75, v0
	v_mov_b32_e32 v80, v0
	v_mov_b32_e32 v81, v0
	v_mov_b32_e32 v82, v0
	v_mov_b32_e32 v83, v0
	v_mov_b32_e32 v88, v0
	v_mov_b32_e32 v89, v0
	v_mov_b32_e32 v90, v0
	v_mov_b32_e32 v91, v0
	v_mov_b32_e32 v96, v0
	v_mov_b32_e32 v97, v0
	v_mov_b32_e32 v98, v0
	v_mov_b32_e32 v99, v0
	v_mov_b32_e32 v104, v0
	v_mov_b32_e32 v105, v0
	v_mov_b32_e32 v106, v0
	v_mov_b32_e32 v107, v0
	v_mov_b32_e32 v112, v0
	v_mov_b32_e32 v113, v0
	v_mov_b32_e32 v114, v0
	v_mov_b32_e32 v115, v0
	v_mov_b32_e32 v76, v0
	v_mov_b32_e32 v77, v0
	v_mov_b32_e32 v78, v0
	v_mov_b32_e32 v79, v0
	v_mov_b32_e32 v84, v0
	v_mov_b32_e32 v85, v0
	v_mov_b32_e32 v86, v0
	v_mov_b32_e32 v87, v0
	v_mov_b32_e32 v92, v0
	v_mov_b32_e32 v93, v0
	v_mov_b32_e32 v94, v0
	v_mov_b32_e32 v95, v0
	v_mov_b32_e32 v100, v0
	v_mov_b32_e32 v101, v0
	v_mov_b32_e32 v102, v0
	v_mov_b32_e32 v103, v0
	v_mov_b32_e32 v108, v0
	v_mov_b32_e32 v109, v0
	v_mov_b32_e32 v110, v0
	v_mov_b32_e32 v111, v0
	v_mov_b32_e32 v116, v0
	v_mov_b32_e32 v117, v0
	v_mov_b32_e32 v118, v0
	v_mov_b32_e32 v119, v0
	v_mov_b32_e32 v120, v0
	v_mov_b32_e32 v121, v0
	v_mov_b32_e32 v122, v0
	v_mov_b32_e32 v123, v0
	v_mov_b32_e32 v124, v0
	v_mov_b32_e32 v125, v0
	v_mov_b32_e32 v126, v0
	v_mov_b32_e32 v127, v0
	.p2align 6

.LBB0_1296:
	s_ashr_i32 s41, s40, 31
	s_xor_b64 s[58:59], s[58:59], -1
	s_xor_b64 s[52:53], s[64:65], -1
	s_lshl_b64 s[48:49], s[40:41], 20
	s_add_u32 s24, s29, s48
	s_addc_u32 s25, s31, s49
	s_ashr_i32 s45, s44, 31
	s_lshl_b64 s[50:51], s[44:45], 7
	s_add_u32 s48, s24, s50
	s_addc_u32 s49, s25, s51
	s_and_b64 s[96:97], s[64:65], exec
	s_cselect_b32 s41, s61, s49
	s_cselect_b32 s45, s60, s48
	s_ashr_i32 s43, s42, 31
	s_lshl_b64 s[96:97], s[42:43], 20
	s_add_u32 s24, s9, s96
	s_addc_u32 s25, s27, s97
	s_add_u32 s50, s24, s50
	s_addc_u32 s51, s25, s51
	s_and_b64 s[64:65], s[64:65], exec
	s_cselect_b32 s43, s63, s51
	s_cselect_b32 s96, s62, s50
	s_add_i32 s97, s91, -2
	s_add_u32 s60, s60, 0x80080
	s_addc_u32 s61, s61, 0
	s_add_u32 vcc_lo, s62, 0x100
	s_addc_u32 vcc_hi, s63, 0
	s_mov_b32 s62, 0
	v_mov_b32_e32 v0, 0
	v_mov_b32_e32 v1, 0
	v_mov_b32_e32 v2, 0
	v_mov_b32_e32 v3, 0
	v_mov_b32_e32 v4, 0
	v_mov_b32_e32 v5, 0
	v_mov_b32_e32 v6, 0
	v_mov_b32_e32 v7, 0
	v_mov_b32_e32 v8, 0
	v_mov_b32_e32 v9, 0
	v_mov_b32_e32 v10, 0
	v_mov_b32_e32 v11, 0
	v_mov_b32_e32 v12, 0
	v_mov_b32_e32 v13, 0
	v_mov_b32_e32 v14, 0
	v_mov_b32_e32 v15, 0
	v_mov_b32_e32 v16, 0
	v_mov_b32_e32 v17, 0
	v_mov_b32_e32 v18, 0
	v_mov_b32_e32 v19, 0
	v_mov_b32_e32 v20, 0
	v_mov_b32_e32 v21, 0
	v_mov_b32_e32 v22, 0
	v_mov_b32_e32 v23, 0
	v_mov_b32_e32 v24, 0
	v_mov_b32_e32 v25, 0
	v_mov_b32_e32 v26, 0
	v_mov_b32_e32 v27, 0
	v_mov_b32_e32 v28, 0
	v_mov_b32_e32 v29, 0
	v_mov_b32_e32 v30, 0
	v_mov_b32_e32 v31, 0
	v_mov_b32_e32 v32, 0
	v_mov_b32_e32 v33, 0
	v_mov_b32_e32 v34, 0
	v_mov_b32_e32 v35, 0
	v_mov_b32_e32 v36, 0
	v_mov_b32_e32 v37, 0
	v_mov_b32_e32 v38, 0
	v_mov_b32_e32 v39, 0
	v_mov_b32_e32 v40, 0
	v_mov_b32_e32 v41, 0
	v_mov_b32_e32 v42, 0
	v_mov_b32_e32 v43, 0
	v_mov_b32_e32 v44, 0
	v_mov_b32_e32 v45, 0
	v_mov_b32_e32 v46, 0
	v_mov_b32_e32 v47, 0
	v_mov_b32_e32 v48, 0
	v_mov_b32_e32 v49, 0
	v_mov_b32_e32 v50, 0
	v_mov_b32_e32 v51, 0
	v_mov_b32_e32 v52, 0
	v_mov_b32_e32 v53, 0
	v_mov_b32_e32 v54, 0
	v_mov_b32_e32 v55, 0
	v_mov_b32_e32 v56, 0
	v_mov_b32_e32 v57, 0
	v_mov_b32_e32 v58, 0
	v_mov_b32_e32 v59, 0
	v_mov_b32_e32 v60, 0
	v_mov_b32_e32 v61, 0
	v_mov_b32_e32 v62, 0
	v_mov_b32_e32 v63, 0
	v_mov_b32_e32 v64, 0
	v_mov_b32_e32 v65, 0
	v_mov_b32_e32 v66, 0
	v_mov_b32_e32 v67, 0
	v_mov_b32_e32 v68, 0
	v_mov_b32_e32 v69, 0
	v_mov_b32_e32 v70, 0
	v_mov_b32_e32 v71, 0
	v_mov_b32_e32 v72, 0
	v_mov_b32_e32 v73, 0
	v_mov_b32_e32 v74, 0
	v_mov_b32_e32 v75, 0
	v_mov_b32_e32 v76, 0
	v_mov_b32_e32 v77, 0
	v_mov_b32_e32 v78, 0
	v_mov_b32_e32 v79, 0
	v_mov_b32_e32 v84, 0
	v_mov_b32_e32 v85, 0
	v_mov_b32_e32 v86, 0
	v_mov_b32_e32 v87, 0
	v_mov_b32_e32 v92, 0
	v_mov_b32_e32 v93, 0
	v_mov_b32_e32 v94, 0
	v_mov_b32_e32 v95, 0
	v_mov_b32_e32 v100, 0
	v_mov_b32_e32 v101, 0
	v_mov_b32_e32 v102, 0
	v_mov_b32_e32 v103, 0
	v_mov_b32_e32 v108, 0
	v_mov_b32_e32 v109, 0
	v_mov_b32_e32 v110, 0
	v_mov_b32_e32 v111, 0
	v_mov_b32_e32 v80, 0
	v_mov_b32_e32 v81, 0
	v_mov_b32_e32 v82, 0
	v_mov_b32_e32 v83, 0
	v_mov_b32_e32 v88, 0
	v_mov_b32_e32 v89, 0
	v_mov_b32_e32 v90, 0
	v_mov_b32_e32 v91, 0
	v_mov_b32_e32 v96, 0
	v_mov_b32_e32 v97, 0
	v_mov_b32_e32 v98, 0
	v_mov_b32_e32 v99, 0
	v_mov_b32_e32 v104, 0
	v_mov_b32_e32 v105, 0
	v_mov_b32_e32 v106, 0
	v_mov_b32_e32 v107, 0
	v_mov_b32_e32 v112, 0
	v_mov_b32_e32 v113, 0
	v_mov_b32_e32 v114, 0
	v_mov_b32_e32 v115, 0
	v_mov_b32_e32 v116, 0
	v_mov_b32_e32 v117, 0
	v_mov_b32_e32 v118, 0
	v_mov_b32_e32 v119, 0
	v_mov_b32_e32 v120, 0
	v_mov_b32_e32 v121, 0
	v_mov_b32_e32 v122, 0
	v_mov_b32_e32 v123, 0
	v_mov_b32_e32 v124, 0
	v_mov_b32_e32 v125, 0
	v_mov_b32_e32 v126, 0
	v_mov_b32_e32 v127, 0
	.p2align 6

.LBB0_1443:
	s_add_i32 s53, s96, -2
	s_add_u32 s97, s60, 0x100
	v_mov_b32_e32 v32, 0
	s_addc_u32 vcc_lo, s61, 0
	s_mov_b32 s62, 0
	v_mov_b32_e32 v33, v32
	v_mov_b32_e32 v34, v32
	v_mov_b32_e32 v35, v32
	v_mov_b32_e32 v36, v32
	v_mov_b32_e32 v37, v32
	v_mov_b32_e32 v38, v32
	v_mov_b32_e32 v39, v32
	v_mov_b32_e32 v44, v32
	v_mov_b32_e32 v45, v32
	v_mov_b32_e32 v46, v32
	v_mov_b32_e32 v47, v32
	v_mov_b32_e32 v48, v32
	v_mov_b32_e32 v49, v32
	v_mov_b32_e32 v50, v32
	v_mov_b32_e32 v51, v32
	v_mov_b32_e32 v60, v32
	v_mov_b32_e32 v61, v32
	v_mov_b32_e32 v62, v32
	v_mov_b32_e32 v63, v32
	v_mov_b32_e32 v64, v32
	v_mov_b32_e32 v65, v32
	v_mov_b32_e32 v66, v32
	v_mov_b32_e32 v67, v32
	v_mov_b32_e32 v76, v32
	v_mov_b32_e32 v77, v32
	v_mov_b32_e32 v78, v32
	v_mov_b32_e32 v79, v32
	v_mov_b32_e32 v80, v32
	v_mov_b32_e32 v81, v32
	v_mov_b32_e32 v82, v32
	v_mov_b32_e32 v83, v32
	v_mov_b32_e32 v40, v32
	v_mov_b32_e32 v41, v32
	v_mov_b32_e32 v42, v32
	v_mov_b32_e32 v43, v32
	v_mov_b32_e32 v52, v32
	v_mov_b32_e32 v53, v32
	v_mov_b32_e32 v54, v32
	v_mov_b32_e32 v55, v32
	v_mov_b32_e32 v56, v32
	v_mov_b32_e32 v57, v32
	v_mov_b32_e32 v58, v32
	v_mov_b32_e32 v59, v32
	v_mov_b32_e32 v68, v32
	v_mov_b32_e32 v69, v32
	v_mov_b32_e32 v70, v32
	v_mov_b32_e32 v71, v32
	v_mov_b32_e32 v72, v32
	v_mov_b32_e32 v73, v32
	v_mov_b32_e32 v74, v32
	v_mov_b32_e32 v75, v32
	v_mov_b32_e32 v84, v32
	v_mov_b32_e32 v85, v32
	v_mov_b32_e32 v86, v32
	v_mov_b32_e32 v87, v32
	v_mov_b32_e32 v88, v32
	v_mov_b32_e32 v89, v32
	v_mov_b32_e32 v90, v32
	v_mov_b32_e32 v91, v32
	v_mov_b32_e32 v92, v32
	v_mov_b32_e32 v93, v32
	v_mov_b32_e32 v94, v32
	v_mov_b32_e32 v95, v32
	v_mov_b32_e32 v96, v32
	v_mov_b32_e32 v97, v32
	v_mov_b32_e32 v98, v32
	v_mov_b32_e32 v99, v32
	v_mov_b32_e32 v100, v32
	v_mov_b32_e32 v101, v32
	v_mov_b32_e32 v102, v32
	v_mov_b32_e32 v103, v32
	v_mov_b32_e32 v104, v32
	v_mov_b32_e32 v105, v32
	v_mov_b32_e32 v106, v32
	v_mov_b32_e32 v107, v32
	v_mov_b32_e32 v112, v32
	v_mov_b32_e32 v113, v32
	v_mov_b32_e32 v114, v32
	v_mov_b32_e32 v115, v32
	v_mov_b32_e32 v120, v32
	v_mov_b32_e32 v121, v32
	v_mov_b32_e32 v122, v32
	v_mov_b32_e32 v123, v32
	v_mov_b32_e32 v128, v32
	v_mov_b32_e32 v129, v32
	v_mov_b32_e32 v130, v32
	v_mov_b32_e32 v131, v32
	v_mov_b32_e32 v136, v32
	v_mov_b32_e32 v137, v32
	v_mov_b32_e32 v138, v32
	v_mov_b32_e32 v139, v32
	v_mov_b32_e32 v144, v32
	v_mov_b32_e32 v145, v32
	v_mov_b32_e32 v146, v32
	v_mov_b32_e32 v147, v32
	v_mov_b32_e32 v108, v32
	v_mov_b32_e32 v109, v32
	v_mov_b32_e32 v110, v32
	v_mov_b32_e32 v111, v32
	v_mov_b32_e32 v116, v32
	v_mov_b32_e32 v117, v32
	v_mov_b32_e32 v118, v32
	v_mov_b32_e32 v119, v32
	v_mov_b32_e32 v124, v32
	v_mov_b32_e32 v125, v32
	v_mov_b32_e32 v126, v32
	v_mov_b32_e32 v127, v32
	v_mov_b32_e32 v132, v32
	v_mov_b32_e32 v133, v32
	v_mov_b32_e32 v134, v32
	v_mov_b32_e32 v135, v32
	v_mov_b32_e32 v140, v32
	v_mov_b32_e32 v141, v32
	v_mov_b32_e32 v142, v32
	v_mov_b32_e32 v143, v32
	v_mov_b32_e32 v148, v32
	v_mov_b32_e32 v149, v32
	v_mov_b32_e32 v150, v32
	v_mov_b32_e32 v151, v32
	v_mov_b32_e32 v152, v32
	v_mov_b32_e32 v153, v32
	v_mov_b32_e32 v154, v32
	v_mov_b32_e32 v155, v32
	v_mov_b32_e32 v156, v32
	v_mov_b32_e32 v157, v32
	v_mov_b32_e32 v158, v32
	v_mov_b32_e32 v159, v32
	.p2align 6

.LBB0_1587:
	s_ashr_i32 s31, s30, 31
	s_xor_b64 s[48:49], s[48:49], -1
	s_xor_b64 s[42:43], s[54:55], -1
	s_lshl_b64 s[38:39], s[30:31], 20
	s_add_u32 s31, s56, s38
	s_addc_u32 s35, s57, s39
	s_ashr_i32 s37, s36, 31
	s_lshl_b64 s[40:41], s[36:37], 7
	s_add_u32 s38, s31, s40
	s_addc_u32 s39, s35, s41
	s_and_b64 s[76:77], s[54:55], exec
	s_cselect_b32 s31, s51, s39
	s_cselect_b32 s37, s50, s38
	s_ashr_i32 s35, s34, 31
	s_lshl_b64 s[76:77], s[34:35], 20
	s_add_u32 s35, s3, s76
	s_addc_u32 s75, s27, s77
	s_add_u32 s40, s35, s40
	s_addc_u32 s41, s75, s41
	s_and_b64 s[54:55], s[54:55], exec
	s_cselect_b32 s35, s53, s41
	s_cselect_b32 s75, s52, s40
	s_add_i32 s76, s45, -2
	s_add_u32 s50, s50, 0x80080
	s_addc_u32 s51, s51, 0
	s_add_u32 s77, s52, 0x100
	v_mov_b32_e32 v32, 0
	s_addc_u32 s78, s53, 0
	s_mov_b32 s52, 0
	v_mov_b32_e32 v33, v32
	v_mov_b32_e32 v34, v32
	v_mov_b32_e32 v35, v32
	v_mov_b32_e32 v36, v32
	v_mov_b32_e32 v37, v32
	v_mov_b32_e32 v38, v32
	v_mov_b32_e32 v39, v32
	v_mov_b32_e32 v40, v32
	v_mov_b32_e32 v41, v32
	v_mov_b32_e32 v42, v32
	v_mov_b32_e32 v43, v32
	v_mov_b32_e32 v48, v32
	v_mov_b32_e32 v49, v32
	v_mov_b32_e32 v50, v32
	v_mov_b32_e32 v51, v32
	v_mov_b32_e32 v60, v32
	v_mov_b32_e32 v61, v32
	v_mov_b32_e32 v62, v32
	v_mov_b32_e32 v63, v32
	v_mov_b32_e32 v64, v32
	v_mov_b32_e32 v65, v32
	v_mov_b32_e32 v66, v32
	v_mov_b32_e32 v67, v32
	v_mov_b32_e32 v76, v32
	v_mov_b32_e32 v77, v32
	v_mov_b32_e32 v78, v32
	v_mov_b32_e32 v79, v32
	v_mov_b32_e32 v80, v32
	v_mov_b32_e32 v81, v32
	v_mov_b32_e32 v82, v32
	v_mov_b32_e32 v83, v32
	v_mov_b32_e32 v44, v32
	v_mov_b32_e32 v45, v32
	v_mov_b32_e32 v46, v32
	v_mov_b32_e32 v47, v32
	v_mov_b32_e32 v52, v32
	v_mov_b32_e32 v53, v32
	v_mov_b32_e32 v54, v32
	v_mov_b32_e32 v55, v32
	v_mov_b32_e32 v56, v32
	v_mov_b32_e32 v57, v32
	v_mov_b32_e32 v58, v32
	v_mov_b32_e32 v59, v32
	v_mov_b32_e32 v68, v32
	v_mov_b32_e32 v69, v32
	v_mov_b32_e32 v70, v32
	v_mov_b32_e32 v71, v32
	v_mov_b32_e32 v72, v32
	v_mov_b32_e32 v73, v32
	v_mov_b32_e32 v74, v32
	v_mov_b32_e32 v75, v32
	v_mov_b32_e32 v84, v32
	v_mov_b32_e32 v85, v32
	v_mov_b32_e32 v86, v32
	v_mov_b32_e32 v87, v32
	v_mov_b32_e32 v88, v32
	v_mov_b32_e32 v89, v32
	v_mov_b32_e32 v90, v32
	v_mov_b32_e32 v91, v32
	v_mov_b32_e32 v92, v32
	v_mov_b32_e32 v93, v32
	v_mov_b32_e32 v94, v32
	v_mov_b32_e32 v95, v32
	v_mov_b32_e32 v96, v32
	v_mov_b32_e32 v97, v32
	v_mov_b32_e32 v98, v32
	v_mov_b32_e32 v99, v32
	v_mov_b32_e32 v100, v32
	v_mov_b32_e32 v101, v32
	v_mov_b32_e32 v102, v32
	v_mov_b32_e32 v103, v32
	v_mov_b32_e32 v104, v32
	v_mov_b32_e32 v105, v32
	v_mov_b32_e32 v106, v32
	v_mov_b32_e32 v107, v32
	v_mov_b32_e32 v112, v32
	v_mov_b32_e32 v113, v32
	v_mov_b32_e32 v114, v32
	v_mov_b32_e32 v115, v32
	v_mov_b32_e32 v120, v32
	v_mov_b32_e32 v121, v32
	v_mov_b32_e32 v122, v32
	v_mov_b32_e32 v123, v32
	v_mov_b32_e32 v128, v32
	v_mov_b32_e32 v129, v32
	v_mov_b32_e32 v130, v32
	v_mov_b32_e32 v131, v32
	v_mov_b32_e32 v136, v32
	v_mov_b32_e32 v137, v32
	v_mov_b32_e32 v138, v32
	v_mov_b32_e32 v139, v32
	v_mov_b32_e32 v144, v32
	v_mov_b32_e32 v145, v32
	v_mov_b32_e32 v146, v32
	v_mov_b32_e32 v147, v32
	v_mov_b32_e32 v108, v32
	v_mov_b32_e32 v109, v32
	v_mov_b32_e32 v110, v32
	v_mov_b32_e32 v111, v32
	v_mov_b32_e32 v116, v32
	v_mov_b32_e32 v117, v32
	v_mov_b32_e32 v118, v32
	v_mov_b32_e32 v119, v32
	v_mov_b32_e32 v124, v32
	v_mov_b32_e32 v125, v32
	v_mov_b32_e32 v126, v32
	v_mov_b32_e32 v127, v32
	v_mov_b32_e32 v132, v32
	v_mov_b32_e32 v133, v32
	v_mov_b32_e32 v134, v32
	v_mov_b32_e32 v135, v32
	v_mov_b32_e32 v140, v32
	v_mov_b32_e32 v141, v32
	v_mov_b32_e32 v142, v32
	v_mov_b32_e32 v143, v32
	v_mov_b32_e32 v148, v32
	v_mov_b32_e32 v149, v32
	v_mov_b32_e32 v150, v32
	v_mov_b32_e32 v151, v32
	v_mov_b32_e32 v152, v32
	v_mov_b32_e32 v153, v32
	v_mov_b32_e32 v154, v32
	v_mov_b32_e32 v155, v32
	v_mov_b32_e32 v156, v32
	v_mov_b32_e32 v157, v32
	v_mov_b32_e32 v158, v32
	v_mov_b32_e32 v159, v32
	.p2align 6
